# mLSTM chunk loop: the two xor-1/2/4 shuffle reductions use DPP moves (quad_perm, row_half_mirror) instead of ds_bpermute round trips
# speedup vs baseline: 1.0166x; 1.0083x over previous
.LBB0_828:
	s_or_b64 exec, exec, s[14:15]
	s_nop 1
	v_cvt_pk_bf16_f32 v60, v1, v63
	s_nop 1
	v_cvt_pk_bf16_f32 v61, v58, v59
	ds_write_b64 v168, v[60:61] offset:2304
	ds_read_b64 v[180:181], v123
	ds_read_b64 v[182:183], v124
	ds_read_u16 v179, v159 offset:17408
	ds_read_u16 v184, v159 offset:17680
	ds_read_u16 v185, v159 offset:17952
	ds_read_u16 v186, v159 offset:18224
	ds_read_b64 v[188:189], v125
	ds_read_u16 v187, v159 offset:18496
	ds_read_u16 v190, v159 offset:18768
	ds_read_b64 v[192:193], v126
	ds_read_u16 v191, v159 offset:19040
	ds_read_u16 v194, v159 offset:19312
	s_waitcnt lgkmcnt(12)
	ds_read_u16 v178, v158 offset:17408
	ds_read_b64 v[196:197], v127
	ds_read_u16 v195, v159 offset:19584
	v_cmp_lt_i32_e32 vcc, v231, v225
	s_and_b32 s35, s35, 1
	s_waitcnt lgkmcnt(2)
	v_lshlrev_b32_e32 v1, 16, v178
	v_mul_f32_e32 v1, v180, v1
	ds_read_u16 v178, v159 offset:19856
	v_lshlrev_b32_e32 v58, 16, v179
	v_mul_f32_e32 v58, v181, v58
	s_nop 1
	v_cvt_pk_bf16_f32 v58, v1, v58
	s_nop 0
	v_lshlrev_b32_e32 v1, 16, v58
	v_and_b32_e32 v59, 0xffff0000, v58
	v_add_f32_e32 v1, v1, v59
	ds_read_b64 v[180:181], v128
	v_add_f32_e32 v1, 0, v1
	v_lshlrev_b32_e32 v59, 16, v184
	v_mul_f32_e32 v59, v182, v59
	ds_read_u16 v179, v159 offset:20128
	v_lshlrev_b32_e32 v60, 16, v185
	v_mul_f32_e32 v60, v183, v60
	s_nop 1
	v_cvt_pk_bf16_f32 v59, v59, v60
	s_nop 0
	v_lshlrev_b32_e32 v60, 16, v59
	v_and_b32_e32 v61, 0xffff0000, v59
	v_add_f32_e32 v60, v60, v61
	v_add_f32_e32 v1, v1, v60
	ds_read_u16 v182, v159 offset:20400
	v_lshlrev_b32_e32 v62, 16, v186
	ds_read_b64 v[184:185], v129
	v_mul_f32_e32 v60, v188, v62
	ds_read_u16 v183, v159 offset:20672
	v_lshlrev_b32_e32 v62, 16, v187
	v_mul_f32_e32 v61, v189, v62
	s_nop 1
	v_cvt_pk_bf16_f32 v60, v60, v61
	s_nop 0
	v_lshlrev_b32_e32 v61, 16, v60
	v_and_b32_e32 v62, 0xffff0000, v60
	v_add_f32_e32 v61, v61, v62
	v_add_f32_e32 v1, v1, v61
	ds_read_u16 v186, v159 offset:20944
	v_lshlrev_b32_e32 v61, 16, v190
	v_mul_f32_e32 v61, v192, v61
	ds_read_u16 v187, v159 offset:21216
	v_lshlrev_b32_e32 v62, 16, v191
	v_mul_f32_e32 v62, v193, v62
	s_nop 1
	v_cvt_pk_bf16_f32 v61, v61, v62
	s_nop 0
	v_lshlrev_b32_e32 v62, 16, v61
	v_and_b32_e32 v63, 0xffff0000, v61
	v_add_f32_e32 v62, v62, v63
	v_add_f32_e32 v1, v1, v62
	v_lshlrev_b32_e32 v64, 16, v194
	s_waitcnt lgkmcnt(9)
	v_mul_f32_e32 v62, v196, v64
	s_waitcnt lgkmcnt(8)
	v_lshlrev_b32_e32 v64, 16, v195
	v_mul_f32_e32 v63, v197, v64
	s_nop 1
	v_cvt_pk_bf16_f32 v62, v62, v63
	s_nop 0
	v_lshlrev_b32_e32 v63, 16, v62
	v_and_b32_e32 v64, 0xffff0000, v62
	v_add_f32_e32 v63, v63, v64
	v_add_f32_e32 v1, v1, v63
	s_waitcnt lgkmcnt(7)
	v_lshlrev_b32_e32 v63, 16, v178
	s_waitcnt lgkmcnt(6)
	v_mul_f32_e32 v63, v180, v63
	s_waitcnt lgkmcnt(5)
	v_lshlrev_b32_e32 v64, 16, v179
	v_mul_f32_e32 v64, v181, v64
	s_nop 1
	v_cvt_pk_bf16_f32 v63, v63, v64
	s_nop 0
	v_lshlrev_b32_e32 v64, 16, v63
	v_and_b32_e32 v65, 0xffff0000, v63
	v_add_f32_e32 v64, v64, v65
	v_add_f32_e32 v1, v1, v64
	s_waitcnt lgkmcnt(4)
	v_lshlrev_b32_e32 v66, 16, v182
	s_waitcnt lgkmcnt(3)
	v_mul_f32_e32 v64, v184, v66
	s_waitcnt lgkmcnt(2)
	v_lshlrev_b32_e32 v66, 16, v183
	v_mul_f32_e32 v65, v185, v66
	s_nop 1
	v_cvt_pk_bf16_f32 v64, v64, v65
	s_nop 0
	v_lshlrev_b32_e32 v65, 16, v64
	v_and_b32_e32 v66, 0xffff0000, v64
	v_add_f32_e32 v65, v65, v66
	v_add_f32_e32 v1, v1, v65
	ds_read_b64 v[66:67], v130
	s_waitcnt lgkmcnt(2)
	v_lshlrev_b32_e32 v65, 16, v186
	s_waitcnt lgkmcnt(0)
	v_mul_f32_e32 v65, v66, v65
	v_lshlrev_b32_e32 v66, 16, v187
	v_mul_f32_e32 v66, v67, v66
	s_nop 1
	v_cvt_pk_bf16_f32 v65, v65, v66
	ds_write_b128 v160, v[58:61] offset:34816
	ds_write_b128 v160, v[62:65] offset:34832
	v_lshlrev_b32_e32 v66, 16, v65
	v_and_b32_e32 v67, 0xffff0000, v65
	v_add_f32_e32 v66, v66, v67
	v_cndmask_b32_e32 v58, v223, v231, vcc
	v_add_f32_e32 v1, v1, v66
	v_lshlrev_b32_e32 v58, 2, v58
	s_nop 1
	v_mov_b32_dpp v59, v1 quad_perm:[1,0,3,2] row_mask:0xf bank_mask:0xf
	v_cmp_lt_i32_e32 vcc, v230, v225
	s_waitcnt lgkmcnt(0)
	v_add_f32_e32 v1, v1, v59
	v_cndmask_b32_e32 v59, v223, v230, vcc
	v_lshlrev_b32_e32 v59, 2, v59
	s_nop 1
	v_mov_b32_dpp v61, v1 quad_perm:[2,3,0,1] row_mask:0xf bank_mask:0xf
	s_and_saveexec_b64 s[14:15], s[44:45]
	s_xor_b64 s[14:15], exec, s[14:15]
	s_lshl_b32 s84, s35, 9
	s_or_saveexec_b64 s[14:15], s[14:15]
	v_mov_b32_e32 v60, s84
	s_xor_b64 exec, exec, s[14:15]
	s_cbranch_execz .LBB0_832
	s_lshl_b32 s35, s35, 9
	s_waitcnt lgkmcnt(0)
	v_add_f32_e32 v1, v1, v61
	v_mov_b32_e32 v60, s29
	v_add_u32_e32 v61, s35, v113
	ds_read_b32 v60, v60
	ds_read_b32 v61, v61
	s_xor_b32 s84, s35, 0x200
	s_waitcnt lgkmcnt(0)
	v_fmac_f32_e32 v1, v60, v61
	v_add_u32_e32 v60, s84, v113
	ds_write_b32 v60, v1
	v_mov_b32_e32 v60, s35
.LBB0_832:
	s_or_b64 exec, exec, s[14:15]
	s_waitcnt lgkmcnt(0)
	s_barrier
	ds_read_b128 v[62:65], v161
	ds_read_b128 v[66:69], v162
	v_add_u32_e32 v1, v107, v60
	v_cmp_lt_i32_e32 vcc, v229, v225
	s_waitcnt lgkmcnt(1)
	v_lshlrev_b32_e32 v86, 16, v62
	v_and_b32_e32 v88, 0xffff0000, v62
	v_lshlrev_b32_e32 v146, 16, v63
	v_and_b32_e32 v148, 0xffff0000, v63
	ds_read_b128 v[60:63], v162 offset:16
	ds_read_b128 v[70:73], v1
	ds_read_b128 v[74:77], v1 offset:16
	ds_read_b128 v[78:81], v1 offset:32
	ds_read_b128 v[82:85], v1 offset:48
	s_waitcnt lgkmcnt(5)
	v_lshlrev_b32_e32 v176, 16, v66
	v_and_b32_e32 v177, 0xffff0000, v66
	s_waitcnt lgkmcnt(4)
	v_and_b32_e32 v66, 0xffff0000, v60
	s_waitcnt lgkmcnt(3)
	v_pk_mul_f32 v[70:71], v[70:71], v[176:177]
	v_mov_b32_e32 v177, v72
	v_add_f32_e32 v1, v70, v71
	v_lshlrev_b32_e32 v71, 16, v67
	v_and_b32_e32 v67, 0xffff0000, v67
	s_waitcnt lgkmcnt(1)
	v_mov_b32_e32 v72, v79
	v_lshlrev_b32_e32 v70, 16, v60
	v_mov_b32_e32 v176, v78
	v_pk_mul_f32 v[66:67], v[72:73], v[66:67]
	v_add_f32_e32 v1, 0, v1
	v_pk_fma_f32 v[66:67], v[176:177], v[70:71], v[66:67]
	v_lshlrev_b32_e32 v60, 16, v61
	v_add_f32_e32 v1, v1, v66
	v_add_f32_e32 v87, v1, v67
	v_lshlrev_b32_e32 v1, 16, v62
	s_waitcnt lgkmcnt(0)
	v_mul_f32_e32 v147, v82, v1
	v_and_b32_e32 v1, 0xffff0000, v62
	v_and_b32_e32 v61, 0xffff0000, v61
	v_mul_f32_e32 v66, v80, v60
	v_mul_f32_e32 v149, v83, v1
	v_lshlrev_b32_e32 v1, 16, v69
	v_pk_fma_f32 v[60:61], v[80:81], v[60:61], v[66:67] op_sel_hi:[1,1,0]
	v_lshlrev_b32_e32 v66, 16, v68
	v_mul_f32_e32 v151, v76, v1
	v_and_b32_e32 v1, 0xffff0000, v69
	v_lshlrev_b32_e32 v152, 16, v65
	v_and_b32_e32 v174, 0xffff0000, v65
	v_and_b32_e32 v67, 0xffff0000, v68
	v_mul_f32_e32 v60, v74, v66
	v_mul_f32_e32 v65, v77, v1
	v_lshlrev_b32_e32 v1, 16, v63
	v_pk_fma_f32 v[66:67], v[74:75], v[66:67], v[60:61] op_sel_hi:[1,1,0]
	v_mul_f32_e32 v153, v84, v1
	v_and_b32_e32 v1, 0xffff0000, v63
	v_mov_b32_e32 v89, v61
	v_mul_f32_e32 v175, v85, v1
	v_pk_add_f32 v[60:61], v[86:87], v[88:89]
	v_mov_b32_e32 v1, v67
	v_lshlrev_b32_e32 v150, 16, v64
	v_and_b32_e32 v64, 0xffff0000, v64
	v_pk_add_f32 v[62:63], v[146:147], v[148:149]
	v_pk_add_f32 v[60:61], v[60:61], v[0:1]
	v_pk_add_f32 v[64:65], v[150:151], v[64:65]
	v_pk_add_f32 v[60:61], v[60:61], v[62:63]
	v_pk_add_f32 v[68:69], v[152:153], v[174:175]
	v_pk_add_f32 v[60:61], v[60:61], v[64:65]
	v_cndmask_b32_e32 v1, v223, v229, vcc
	v_pk_add_f32 v[60:61], v[60:61], v[68:69]
	s_nop 1
	v_mov_b32_dpp v62, v60 quad_perm:[1,0,3,2] row_mask:0xf bank_mask:0xf
	s_nop 1
	v_mov_b32_dpp v63, v61 quad_perm:[1,0,3,2] row_mask:0xf bank_mask:0xf
	v_lshlrev_b32_e32 v1, 2, v1
	s_waitcnt lgkmcnt(0)
	v_pk_add_f32 v[60:61], v[60:61], v[62:63]
	s_nop 1
	v_mov_b32_dpp v58, v60 quad_perm:[2,3,0,1] row_mask:0xf bank_mask:0xf
	s_nop 1
	v_mov_b32_dpp v59, v61 quad_perm:[2,3,0,1] row_mask:0xf bank_mask:0xf
	s_waitcnt lgkmcnt(0)
	v_pk_add_f32 v[58:59], v[60:61], v[58:59]
	s_nop 1
	v_mov_b32_dpp v60, v58 row_half_mirror row_mask:0xf bank_mask:0xf
	s_nop 1
	v_mov_b32_dpp v61, v59 row_half_mirror row_mask:0xf bank_mask:0xf
	s_and_saveexec_b64 s[14:15], s[46:47]
	s_cbranch_execz .LBB0_834
	ds_read_b32 v1, v115
	s_waitcnt lgkmcnt(1)
	v_pk_add_f32 v[58:59], v[58:59], v[60:61]
	s_waitcnt lgkmcnt(0)
	v_fmac_f32_e32 v58, v59, v1
	ds_write_b32 v114, v58
